# first grid barrier's 16 XCD counter reads issued together (one base + immediate offsets); attention unit prologue issues the skip-bound word and first K/V tile loads with the Q loads
# baseline (speedup 1.0000x reference)
; __device__ __forceinline__ unsigned xb_ld(unsigned* p)              { return __hip_atomic_load(p, __ATOMIC_RELAXED, __HIP_MEMORY_SCOPE_AGENT); }
; __device__ __forceinline__ void xcd_barrier_complete(unsigned* bar, unsigned x, unsigned& nloc, unsigned& nx) {
;     const unsigned G = gridDim.x * gridDim.y * gridDim.z;
;     unsigned sum, cnt, mine, sp = 0u;
;     for (;;) {
;         sum = 0u; cnt = 0u; mine = 0u;
; #pragma unroll
;         for (unsigned j = 0; j < 16; ++j) { const unsigned c = xb_ld(&bar[XB_XCNT(j)]); sum += c; cnt += (c > 0u) ? 1u : 0u; mine = (j == x) ? c : mine; }
;         if (sum == G) break;
;         __builtin_amdgcn_s_sleep(1);
;         if ((++sp & 255u) == 0u) { if (xb_ld(&bar[XB_TMO])) break; if (sp > XB_SPIN_CAP) { atomicAdd(&bar[XB_TMO], 1u); break; } }
;     }
;     nloc = mine > 0u ? mine : 1u; nx = cnt > 0u ? cnt : 1u;
; }
.LBB0_210:
	global_load_dword v0, v1, s[60:61] sc1
	global_load_dword v2, v1, s[60:61] offset:256 sc1
	global_load_dword v3, v1, s[60:61] offset:512 sc1
	global_load_dword v4, v1, s[60:61] offset:768 sc1
	global_load_dword v5, v1, s[60:61] offset:1024 sc1
	global_load_dword v6, v1, s[60:61] offset:1280 sc1
	global_load_dword v7, v1, s[60:61] offset:1536 sc1
	global_load_dword v8, v1, s[60:61] offset:1792 sc1
	global_load_dword v9, v1, s[60:61] offset:2048 sc1
	global_load_dword v10, v1, s[60:61] offset:2304 sc1
	global_load_dword v11, v1, s[60:61] offset:2560 sc1
	global_load_dword v12, v1, s[60:61] offset:2816 sc1
	global_load_dword v13, v1, s[60:61] offset:3072 sc1
	global_load_dword v14, v1, s[60:61] offset:3328 sc1
	global_load_dword v15, v1, s[60:61] offset:3584 sc1
	global_load_dword v16, v1, s[60:61] offset:3840 sc1
	s_mov_b64 s[16:17], -1
	s_mov_b64 s[18:19], -1
	s_waitcnt vmcnt(0) lgkmcnt(0)
	v_add_u32_e32 v17, v2, v0
	v_add_u32_e32 v17, v17, v3
	v_add_u32_e32 v17, v17, v4
	v_add_u32_e32 v17, v17, v5
	v_add_u32_e32 v17, v17, v6
	v_add_u32_e32 v17, v17, v7
	v_add_u32_e32 v17, v17, v8
	v_add_u32_e32 v17, v17, v9
	v_add_u32_e32 v17, v17, v10
	v_add_u32_e32 v17, v17, v11
	v_add_u32_e32 v17, v17, v12
	v_add_u32_e32 v17, v17, v13
	v_add_u32_e32 v17, v17, v14
	v_add_u32_e32 v17, v17, v15
	v_add_u32_e32 v17, v17, v16
	v_cmp_eq_u32_e32 vcc, s33, v17
	s_cbranch_vccnz .LBB0_209
	s_and_b32 s1, s0, 0xff
	s_cmp_eq_u32 s1, 0
	s_mov_b64 s[20:21], -1
	s_sleep 1
	s_cbranch_scc1 .LBB0_214
	s_and_b64 vcc, exec, s[20:21]
	s_cbranch_vccz .LBB0_209

; #define LAS __attribute__((address_space(3)))
; __device__ __forceinline__ float bf_lo(unsigned w) { return __uint_as_float(w << 16); }
; __device__ __forceinline__ float bf_hi(unsigned w) { return __uint_as_float(w & 0xffff0000u); }
; __device__ __forceinline__ unsigned scale_pk(unsigned w, float c) { return cvt_pk_bf16(bf_lo(w) * c, bf_hi(w) * c); }
; __device__ __forceinline__ void attn_unit(LAS unsigned char* lds, const bf16_t* __restrict__ proj, bf16_t* __restrict__ y, int b, int h, int qb,
;                                           float lam, const float* __restrict__ subln, float post_scale, const unsigned* __restrict__ kmax2) {
;     int tid = threadIdx.x; asm volatile("" : "+v"(tid));
;     const int lane = tid & 63, wid = __builtin_amdgcn_readfirstlane(tid >> 6);
;     const int map = wid & 1, g = wid >> 1, r = lane & 31, hh = lane >> 5;
;     const int g16 = (lane >> 4) & 1, q4 = (lane & 15) >> 2, p4 = lane & 3;
;     const size_t rowbase = (size_t)b * LTOK; const int q0 = qb * CH;
;     const int qpos = q0 + g * 32 + r;
;     const float slope = __builtin_amdgcn_exp2f(-(float)(h + 1));
;     const float c1 = 0.125f * LOG2E, c2 = slope * LOG2E;
;     bf16x8 qf[4];
;     float qn2 = 0.f;
;     { const bf16_t* qp = proj + (rowbase + qpos) * DIN + C_AQ + h * 128 + map * 64 + hh * 8;
; #pragma unroll
;       for (int s = 0; s < 4; ++s) { u32x4 w = *(const u32x4*)(qp + s * 16); w.x = scale_pk(w.x, c1); w.y = scale_pk(w.y, c1); w.z = scale_pk(w.z, c1); w.w = scale_pk(w.w, c1); qf[s] = __builtin_bit_cast(bf16x8, w);
; #pragma unroll
;           for (int k = 0; k < 4; ++k) { const float lo = bf_lo(w[k]), hi = bf_hi(w[k]); qn2 += lo * lo + hi * hi; } } }
;     qn2 += __shfl_xor(qn2, 32);
;     const float ub0 = sqrtf(qn2) * sqrtf(__uint_as_float(kmax2[(b * 8 + h) * 2 + map])) * 1.002f + 1.0f + c2 * (float)(63 - qpos) + 160.0f;
;     LAS volatile unsigned char* FLG = (LAS volatile unsigned char*)(lds + LDS_MISC + 96);
;     f32x16 o[4];
; #pragma unroll
;     for (int t = 0; t < 4; ++t) o[t] = zero16();
;     float m_ref = 0.f, l_run = 0.f;
;     const int jend = 2 * qb + 1;
;     const int skey = tid >> 4, sc = tid & 15;
;     const bf16_t* kg = proj + (rowbase + skey) * DIN + C_AK + h * 128 + sc * 8;
;     const bf16_t* vg = proj + (rowbase + skey) * DIN + C_AV + h * 128 + sc * 8;
;     u32x4 kreg[2], vreg[2];
.LBB0_396:
	s_and_b64 vcc, exec, s[14:15]
	s_cbranch_vccz .LBB0_383
	s_add_i32 s1, s0, 0xfffffdf0
	s_cmpk_lt_i32 s0, 0x100
	s_cselect_b32 s0, s0, s1
	v_mov_b32_e32 v34, v208
	s_and_b32 s11, s0, 3
	s_bfe_u32 s20, s0, 0x30002
	s_ashr_i32 s21, s0, 5
	s_sub_i32 s10, 32, s21
	v_readfirstlane_b32 s0, v34
	s_ashr_i32 s3, s0, 7
	s_ashr_i32 s22, s0, 6
	s_lshl_b32 s1, s10, 7
	s_lshl_b32 s0, s3, 5
	v_and_b32_e32 v185, 31, v34
	s_add_i32 s14, s0, s1
	v_or_b32_e32 v162, s14, v185
	s_mul_i32 s8, s11, 0x1080
	v_ashrrev_i32_e32 v163, 31, v162
	v_lshl_add_u64 v[4:5], v[162:163], 0, s[8:9]
	v_mov_b64_e32 v[2:3], s[6:7]
	v_mad_u64_u32 v[8:9], s[14:15], v4, s35, v[2:3]
	s_and_b32 s2, s22, 1
	v_mad_i32_i24 v9, v5, s35, v9
	s_lshl_b32 s16, s20, 8
	s_mov_b32 s17, s9
	v_bfe_u32 v6, v34, 5, 1
	v_lshl_add_u64 v[4:5], v[8:9], 0, s[16:17]
	s_lshl_b32 s14, s2, 7
	s_mov_b32 s15, s9
	v_lshl_add_u64 v[4:5], v[4:5], 0, s[14:15]
	v_lshlrev_b32_e32 v0, 4, v6
	v_lshl_add_u64 v[4:5], v[4:5], 0, v[0:1]
	global_load_dwordx4 v[8:11], v[4:5], off
	global_load_dwordx4 v[228:231], v[4:5], off offset:32
	global_load_dwordx4 v[232:235], v[4:5], off offset:64
	global_load_dwordx4 v[236:239], v[4:5], off offset:96
	s_lshl_b32 s11, s11, 4
	s_lshl_b32 s15, s20, 1
	s_or_b32 s11, s15, s11
	s_or_b32 s11, s2, s11
	s_lshl_b32 s11, s11, 2
	v_and_b32_e32 v35, 15, v34
	s_lshl_b32 s10, s10, 1
	v_mov_b32_e32 v240, s11
	v_ashrrev_i32_e32 v242, 4, v34
	global_load_dword v36, v240, s[54:55]
	v_add_u32_e32 v240, s8, v242
	v_mad_i64_i32 v[2:3], s[18:19], v240, s35, v[2:3]
	s_or_b32 s11, s10, 1
	v_lshl_add_u64 v[2:3], v[2:3], 0, s[16:17]
	v_lshlrev_b32_e32 v240, 4, v35
	v_mov_b32_e32 v241, v1
	v_lshl_add_u64 v[164:165], v[2:3], 0, v[240:241]
	s_lshl_b32 s15, s11, 6
	v_mad_i64_i32 v[2:3], s[16:17], s15, v213, v[164:165]
	s_or_b32 s18, s15, 32
	global_load_dwordx4 v[128:131], v[2:3], off offset:2048
	v_mad_i64_i32 v[2:3], s[16:17], s18, v213, v[164:165]
	s_mov_b64 s[16:17], 0x1000
	s_nop 0
	v_lshl_add_u64 v[166:167], v[164:165], 0, s[16:17]
	global_load_dwordx4 v[132:135], v[2:3], off offset:2048
	v_mad_i64_i32 v[2:3], s[16:17], s15, v213, v[166:167]
	global_load_dwordx4 v[136:139], v[2:3], off
	v_mad_i64_i32 v[2:3], s[16:17], s18, v213, v[166:167]
	global_load_dwordx4 v[140:143], v[2:3], off
	s_waitcnt vmcnt(8)
	v_lshlrev_b32_e32 v7, 16, v8
	v_and_b32_e32 v8, 0xffff0000, v8
	v_mul_f32_e32 v8, 0x3e38aa3b, v8
	v_mul_f32_e32 v7, 0x3e38aa3b, v7
	v_cvt_pk_bf16_f32 v112, v7, v8
	v_and_b32_e32 v8, 0xffff0000, v9
	v_lshlrev_b32_e32 v7, 16, v9
	v_mul_f32_e32 v8, 0x3e38aa3b, v8
	v_mul_f32_e32 v7, 0x3e38aa3b, v7
	v_cvt_pk_bf16_f32 v113, v7, v8
	v_and_b32_e32 v8, 0xffff0000, v10
	v_lshlrev_b32_e32 v7, 16, v10
	v_mul_f32_e32 v8, 0x3e38aa3b, v8
	v_mul_f32_e32 v7, 0x3e38aa3b, v7
	v_cvt_pk_bf16_f32 v114, v7, v8
	v_and_b32_e32 v8, 0xffff0000, v11
	v_lshlrev_b32_e32 v7, 16, v11
	v_mul_f32_e32 v8, 0x3e38aa3b, v8
	v_mul_f32_e32 v7, 0x3e38aa3b, v7
	v_cvt_pk_bf16_f32 v115, v7, v8
	v_and_b32_e32 v8, 0xffff0000, v112
	v_lshlrev_b32_e32 v7, 16, v112
	v_mul_f32_e32 v8, v8, v8
	v_and_b32_e32 v9, 0xffff0000, v113
	v_fmac_f32_e32 v8, v7, v7
	v_lshlrev_b32_e32 v7, 16, v113
	v_mul_f32_e32 v9, v9, v9
	v_fmac_f32_e32 v9, v7, v7
	v_add_f32_e32 v7, v8, v9
	v_and_b32_e32 v9, 0xffff0000, v114
	v_lshlrev_b32_e32 v8, 16, v114
	v_mul_f32_e32 v9, v9, v9
	v_fmac_f32_e32 v9, v8, v8
	v_add_f32_e32 v7, v7, v9
	v_and_b32_e32 v9, 0xffff0000, v115
	v_lshlrev_b32_e32 v8, 16, v115
	v_mul_f32_e32 v9, v9, v9
	v_fmac_f32_e32 v9, v8, v8
	v_add_f32_e32 v7, v7, v9
	s_waitcnt vmcnt(7)
	v_mov_b32_e32 v8, v228
	v_mov_b32_e32 v9, v229
	v_mov_b32_e32 v10, v230
	v_mov_b32_e32 v11, v231
	v_lshlrev_b32_e32 v12, 16, v8
	v_and_b32_e32 v8, 0xffff0000, v8
	v_mul_f32_e32 v8, 0x3e38aa3b, v8
	v_mul_f32_e32 v12, 0x3e38aa3b, v12
	v_cvt_pk_bf16_f32 v116, v12, v8
	v_lshlrev_b32_e32 v8, 16, v9
	v_and_b32_e32 v9, 0xffff0000, v9
	v_mul_f32_e32 v9, 0x3e38aa3b, v9
	v_mul_f32_e32 v8, 0x3e38aa3b, v8
	v_cvt_pk_bf16_f32 v117, v8, v9
	v_and_b32_e32 v9, 0xffff0000, v10
	v_lshlrev_b32_e32 v8, 16, v10
	v_mul_f32_e32 v9, 0x3e38aa3b, v9
	v_mul_f32_e32 v8, 0x3e38aa3b, v8
	v_cvt_pk_bf16_f32 v118, v8, v9
	v_and_b32_e32 v9, 0xffff0000, v11
	v_lshlrev_b32_e32 v8, 16, v11
	v_mul_f32_e32 v9, 0x3e38aa3b, v9
	v_mul_f32_e32 v8, 0x3e38aa3b, v8
	v_cvt_pk_bf16_f32 v119, v8, v9
	v_and_b32_e32 v9, 0xffff0000, v116
	v_lshlrev_b32_e32 v8, 16, v116
	v_mul_f32_e32 v9, v9, v9
	v_fmac_f32_e32 v9, v8, v8
	v_add_f32_e32 v7, v7, v9
	v_and_b32_e32 v9, 0xffff0000, v117
	v_lshlrev_b32_e32 v8, 16, v117
	v_mul_f32_e32 v9, v9, v9
	v_fmac_f32_e32 v9, v8, v8
	v_add_f32_e32 v7, v7, v9
	v_and_b32_e32 v9, 0xffff0000, v118
	v_lshlrev_b32_e32 v8, 16, v118
	v_mul_f32_e32 v9, v9, v9
	v_fmac_f32_e32 v9, v8, v8
	v_add_f32_e32 v7, v7, v9
	v_and_b32_e32 v9, 0xffff0000, v119
	v_lshlrev_b32_e32 v8, 16, v119
	v_mul_f32_e32 v9, v9, v9
	v_fmac_f32_e32 v9, v8, v8
	v_add_f32_e32 v7, v7, v9
	s_waitcnt vmcnt(6)
; #define LAS __attribute__((address_space(3)))
; __device__ __forceinline__ float bf_lo(unsigned w) { return __uint_as_float(w << 16); }
; __device__ __forceinline__ float bf_hi(unsigned w) { return __uint_as_float(w & 0xffff0000u); }
; #define ATT_BAR() asm volatile("s_waitcnt lgkmcnt(0)\n\ts_barrier" ::: "memory")
; __device__ __forceinline__ unsigned scale_pk(unsigned w, float c) { return cvt_pk_bf16(bf_lo(w) * c, bf_hi(w) * c); }
; #define LOADK(j) do { _Pragma("unroll") for (int i_ = 0; i_ < 2; ++i_) kreg[i_] = *(const u32x4*)(kg + (size_t)((j) * 64 + 32 * i_) * DIN); } while (0)
; __device__ __forceinline__ void attn_unit(LAS unsigned char* lds, const bf16_t* __restrict__ proj, bf16_t* __restrict__ y, int b, int h, int qb,
;                                           float lam, const float* __restrict__ subln, float post_scale, const unsigned* __restrict__ kmax2) {
;     ...
;     { const bf16_t* qp = proj + (rowbase + qpos) * DIN + C_AQ + h * 128 + map * 64 + hh * 8;
; #pragma unroll
;       for (int s = 0; s < 4; ++s) { u32x4 w = *(const u32x4*)(qp + s * 16); w.x = scale_pk(w.x, c1); w.y = scale_pk(w.y, c1); w.z = scale_pk(w.z, c1); w.w = scale_pk(w.w, c1); qf[s] = __builtin_bit_cast(bf16x8, w);
; #pragma unroll
;           for (int k = 0; k < 4; ++k) { const float lo = bf_lo(w[k]), hi = bf_hi(w[k]); qn2 += lo * lo + hi * hi; } } }
;     qn2 += __shfl_xor(qn2, 32);
;     const float ub0 = sqrtf(qn2) * sqrtf(__uint_as_float(kmax2[(b * 8 + h) * 2 + map])) * 1.002f + 1.0f + c2 * (float)(63 - qpos) + 160.0f;
;     LAS volatile unsigned char* FLG = (LAS volatile unsigned char*)(lds + LDS_MISC + 96);
;     f32x16 o[4];
; #pragma unroll
;     for (int t = 0; t < 4; ++t) o[t] = zero16();
;     float m_ref = 0.f, l_run = 0.f;
;     const int jend = 2 * qb + 1;
;     const int skey = tid >> 4, sc = tid & 15;
;     const bf16_t* kg = proj + (rowbase + skey) * DIN + C_AK + h * 128 + sc * 8;
;     const bf16_t* vg = proj + (rowbase + skey) * DIN + C_AV + h * 128 + sc * 8;
;     u32x4 kreg[2], vreg[2];
;     ...
;     const int kAo = r * KSTR + map * 128 + hh * 16;
;     const int vAo = L_VRING + (4 * hh + q4) * VSTR + 32 * g16 + 8 * p4;
;     f32x16 s0, s1; float mx;
;     ...
;     bf16x8 pb[4];
;     LOADK(jend); LOADV(jend);
;     ATT_BAR();
;     STOREK(jend); STOREV(jend);
;     if (jend >= 2) LOADK(jend - 1);
;     if (lane == 0) { FLG[wid] = 0; FLG[8 + wid] = 0; }
;     ATT_BAR();
	v_mov_b32_e32 v8, v232
	v_mov_b32_e32 v9, v233
	v_mov_b32_e32 v10, v234
	v_mov_b32_e32 v11, v235
	v_lshlrev_b32_e32 v12, 16, v8
	v_and_b32_e32 v8, 0xffff0000, v8
	v_mul_f32_e32 v8, 0x3e38aa3b, v8
	v_mul_f32_e32 v12, 0x3e38aa3b, v12
	v_cvt_pk_bf16_f32 v120, v12, v8
	v_lshlrev_b32_e32 v8, 16, v9
	v_and_b32_e32 v9, 0xffff0000, v9
	v_mul_f32_e32 v9, 0x3e38aa3b, v9
	v_mul_f32_e32 v8, 0x3e38aa3b, v8
	v_cvt_pk_bf16_f32 v121, v8, v9
	v_and_b32_e32 v9, 0xffff0000, v10
	v_lshlrev_b32_e32 v8, 16, v10
	v_mul_f32_e32 v9, 0x3e38aa3b, v9
	v_mul_f32_e32 v8, 0x3e38aa3b, v8
	v_cvt_pk_bf16_f32 v122, v8, v9
	v_and_b32_e32 v9, 0xffff0000, v11
	v_lshlrev_b32_e32 v8, 16, v11
	v_mul_f32_e32 v9, 0x3e38aa3b, v9
	v_mul_f32_e32 v8, 0x3e38aa3b, v8
	v_cvt_pk_bf16_f32 v123, v8, v9
	v_and_b32_e32 v9, 0xffff0000, v120
	v_lshlrev_b32_e32 v8, 16, v120
	v_mul_f32_e32 v9, v9, v9
	v_fmac_f32_e32 v9, v8, v8
	v_add_f32_e32 v7, v7, v9
	v_and_b32_e32 v9, 0xffff0000, v121
	v_lshlrev_b32_e32 v8, 16, v121
	v_mul_f32_e32 v9, v9, v9
	v_fmac_f32_e32 v9, v8, v8
	v_add_f32_e32 v7, v7, v9
	v_and_b32_e32 v9, 0xffff0000, v122
	v_lshlrev_b32_e32 v8, 16, v122
	v_mul_f32_e32 v9, v9, v9
	v_fmac_f32_e32 v9, v8, v8
	v_add_f32_e32 v7, v7, v9
	v_and_b32_e32 v9, 0xffff0000, v123
	v_lshlrev_b32_e32 v8, 16, v123
	v_mul_f32_e32 v9, v9, v9
	v_fmac_f32_e32 v9, v8, v8
	v_add_f32_e32 v7, v7, v9
	s_waitcnt vmcnt(5)
	v_mov_b32_e32 v8, v236
	v_mov_b32_e32 v9, v237
	v_mov_b32_e32 v10, v238
	v_mov_b32_e32 v11, v239
	v_and_b32_e32 v5, 0xffff0000, v8
	v_lshlrev_b32_e32 v4, 16, v8
	v_mul_f32_e32 v5, 0x3e38aa3b, v5
	v_mul_f32_e32 v4, 0x3e38aa3b, v4
	v_cvt_pk_bf16_f32 v124, v4, v5
	v_and_b32_e32 v5, 0xffff0000, v9
	v_lshlrev_b32_e32 v4, 16, v9
	v_mul_f32_e32 v5, 0x3e38aa3b, v5
	v_mul_f32_e32 v4, 0x3e38aa3b, v4
	v_cvt_pk_bf16_f32 v125, v4, v5
	v_and_b32_e32 v5, 0xffff0000, v10
	v_lshlrev_b32_e32 v4, 16, v10
	v_mul_f32_e32 v5, 0x3e38aa3b, v5
	v_mul_f32_e32 v4, 0x3e38aa3b, v4
	v_cvt_pk_bf16_f32 v126, v4, v5
	v_and_b32_e32 v5, 0xffff0000, v11
	v_lshlrev_b32_e32 v4, 16, v11
	v_mul_f32_e32 v5, 0x3e38aa3b, v5
	v_mul_f32_e32 v4, 0x3e38aa3b, v4
	v_cvt_pk_bf16_f32 v127, v4, v5
	v_and_b32_e32 v5, 0xffff0000, v124
	v_lshlrev_b32_e32 v4, 16, v124
	v_mul_f32_e32 v5, v5, v5
	v_fmac_f32_e32 v5, v4, v4
	v_add_f32_e32 v4, v7, v5
	v_and_b32_e32 v7, 0xffff0000, v125
	v_lshlrev_b32_e32 v5, 16, v125
	v_mul_f32_e32 v7, v7, v7
	v_fmac_f32_e32 v7, v5, v5
	v_add_f32_e32 v4, v4, v7
	v_and_b32_e32 v7, 0xffff0000, v126
	v_lshlrev_b32_e32 v5, 16, v126
	v_mul_f32_e32 v7, v7, v7
	v_fmac_f32_e32 v7, v5, v5
	v_add_f32_e32 v4, v4, v7
	v_and_b32_e32 v7, 0xffff0000, v127
	v_lshlrev_b32_e32 v5, 16, v127
	v_mul_f32_e32 v7, v7, v7
	v_fmac_f32_e32 v7, v5, v5
	v_add_f32_e32 v37, v4, v7
	v_mov_b32_e32 v4, v240
	v_mov_b32_e32 v5, v241
	v_mov_b32_e32 v7, v242
	ds_bpermute_b32 v38, v215, v37
	s_movk_i32 s16, 0x110
	s_waitcnt lgkmcnt(0)
	s_barrier
	v_add_u32_e32 v186, 0, v4
	v_mul_lo_u32 v187, v7, s16
	v_mul_lo_u32 v188, v7, s75
	v_add_u32_e32 v39, v186, v187
	v_add_u32_e32 v2, v186, v188
	s_cmp_lt_i32 s21, 32
	s_waitcnt vmcnt(3)
	ds_write_b128 v39, v[128:131] offset:17408
	s_waitcnt vmcnt(2)
	ds_write_b128 v39, v[132:135] offset:26112
	s_cselect_b64 s[16:17], -1, 0
	s_cmp_gt_i32 s21, 31
	s_waitcnt vmcnt(1)
	ds_write_b128 v2, v[136:139] offset:55296
	v_add_u32_e32 v2, 0x10000, v2
	s_waitcnt vmcnt(0)
	ds_write_b128 v2, v[140:143]
	s_cbranch_scc1 .LBB0_399
	v_mad_u64_u32 v[2:3], s[18:19], s1, v213, v[164:165]
	s_or_b32 s18, s1, 32
	s_nop 0
	v_mad_u64_u32 v[4:5], s[18:19], s18, v213, v[164:165]
	global_load_dwordx4 v[128:131], v[2:3], off offset:2048
	global_load_dwordx4 v[132:135], v[4:5], off offset:2048
